# nt cache policy on XN1 row loads (read-once stream keeps GEMM operands in L2/MALL)
# speedup vs baseline: 1.0107x; 1.0107x over previous
; __device__ __forceinline__ unsigned pk2(float lo, float hi) { unsigned r; asm volatile("v_cvt_pk_bf16_f32 %0, %1, %2" : "=v"(r) : "v"(lo), "v"(hi)); return r; }
; __device__ __forceinline__ void xn_phase(const Params& p, int layer, int which, char* smem) {
;     ...
;     for (int row = blockIdx.x * 8 + wid; row < nrows; row += gridDim.x * 8) {
;         const bool isc = row >= SEQ; const float* src = isc ? csrc + (size_t)(row - SEQ) * DM : lsrc + (size_t)row * DM;
;         const float* sh = sv + (isc ? 4096 : 0); const float* sc = sh + 2048;
;         f32x4 v[8]; float ss = 0.f;
; #pragma unroll
;         for (int j = 0; j < 8; ++j) { v[j] = *(const f32x4*)(src + 4 * (lane + 64 * j)); ss += (v[j][0] * v[j][0] + v[j][1] * v[j][1]) + (v[j][2] * v[j][2] + v[j][3] * v[j][3]); }
;         const float rinv = rsqrtf(wave_sum(ss) * (1.f / DM) + 1e-6f);
; #pragma unroll
;         for (int j = 0; j < 8; ++j) { const int c = 4 * (lane + 64 * j); const f32x4 gg = *(const f32x4*)(g + c); float y[4];
; #pragma unroll
;             for (int e = 0; e < 4; ++e) y[e] = v[j][e] * rinv * gg[e] * (1.f + sc[c + e]) + sh[c + e];
;             u32x2 o; o.x = pk2(y[0], y[1]); o.y = pk2(y[2], y[3]); *(u32x2*)(XN + (size_t)row * DM + c) = o; }
.LBB0_96:
	s_or_b64 exec, exec, s[14:15]
	v_mov_b32_e32 v45, v1
	v_mov_b32_e32 v47, v1
	v_lshl_add_u64 v[76:77], v[2:3], 0, v[44:45]
	v_lshl_add_u64 v[78:79], v[2:3], 0, v[46:47]
	global_load_dwordx4 v[64:67], v[76:77], off nt
	global_load_dwordx4 v[26:29], v[76:77], off offset:1024 nt
	global_load_dwordx4 v[22:25], v[76:77], off offset:2048 nt
	global_load_dwordx4 v[14:17], v[76:77], off offset:3072 nt
	global_load_dwordx4 v[18:21], v[78:79], off nt
	global_load_dwordx4 v[6:9], v[78:79], off offset:1024 nt
	global_load_dwordx4 v[10:13], v[78:79], off offset:2048 nt
	global_load_dwordx4 v[2:5], v[78:79], off offset:3072 nt
	s_mov_b32 s0, 0x800000
	v_add_u32_e32 v0, s95, v0
	s_waitcnt vmcnt(0)
	v_mul_f32_e32 v68, v64, v64
	v_mul_f32_e32 v69, v65, v65
	v_mul_f32_e32 v70, v66, v66
	v_mul_f32_e32 v71, v67, v67
	v_fmac_f32_e32 v68, v26, v26
	v_fmac_f32_e32 v69, v27, v27
	v_fmac_f32_e32 v70, v28, v28
	v_fmac_f32_e32 v71, v29, v29
	v_fmac_f32_e32 v68, v22, v22
	v_fmac_f32_e32 v69, v23, v23
	v_fmac_f32_e32 v70, v24, v24
	v_fmac_f32_e32 v71, v25, v25
	v_fmac_f32_e32 v68, v14, v14
	v_fmac_f32_e32 v69, v15, v15
	v_fmac_f32_e32 v70, v16, v16
	v_fmac_f32_e32 v71, v17, v17
	v_fmac_f32_e32 v68, v18, v18
	v_fmac_f32_e32 v69, v19, v19
	v_fmac_f32_e32 v70, v20, v20
	v_fmac_f32_e32 v71, v21, v21
	v_fmac_f32_e32 v68, v6, v6
	v_fmac_f32_e32 v69, v7, v7
	v_fmac_f32_e32 v70, v8, v8
	v_fmac_f32_e32 v71, v9, v9
	v_fmac_f32_e32 v68, v10, v10
	v_fmac_f32_e32 v69, v11, v11
	v_fmac_f32_e32 v70, v12, v12
	v_fmac_f32_e32 v71, v13, v13
	v_fmac_f32_e32 v68, v2, v2
	v_fmac_f32_e32 v69, v3, v3
	v_fmac_f32_e32 v70, v4, v4
	v_fmac_f32_e32 v71, v5, v5
	v_add_f32_e32 v68, v68, v69
	v_add_f32_e32 v70, v70, v71
	v_add_f32_e32 v45, v68, v70
	ds_bpermute_b32 v47, v56, v45
	s_waitcnt lgkmcnt(0)
	v_add_f32_e32 v45, v45, v47
	ds_bpermute_b32 v47, v57, v45
	s_waitcnt lgkmcnt(0)
	v_add_f32_e32 v45, v45, v47
	ds_bpermute_b32 v47, v58, v45
	s_waitcnt lgkmcnt(0)
	v_add_f32_e32 v45, v45, v47
	ds_bpermute_b32 v47, v59, v45
	s_waitcnt lgkmcnt(0)
	v_add_f32_e32 v45, v45, v47
	ds_bpermute_b32 v47, v60, v45
	s_waitcnt lgkmcnt(0)
	v_add_f32_e32 v45, v45, v47
	ds_bpermute_b32 v47, v61, v45
	s_waitcnt lgkmcnt(0)
	v_add_f32_e32 v45, v45, v47
	v_fmamk_f32 v45, v45, 0x3a000000, v199
	v_mul_f32_e32 v47, 0x4b800000, v45
	v_cmp_gt_f32_e32 vcc, s0, v45
	s_movk_i32 s0, 0x40ff
	s_nop 0
	v_cndmask_b32_e32 v45, v45, v47, vcc
	v_rsq_f32_e32 v45, v45
	s_nop 0
	v_mul_f32_e32 v47, 0x45800000, v45
	v_cndmask_b32_e32 v45, v45, v47, vcc
	v_mul_f32_e32 v47, v64, v45
	v_mul_f32_e32 v49, v65, v45
	v_mul_f32_e32 v51, v66, v45
	v_mul_f32_e32 v53, v67, v45
	v_mul_f32_e32 v28, v28, v45
	v_mul_f32_e32 v29, v29, v45
	v_mul_f32_e32 v18, v18, v45
	v_mul_f32_e32 v19, v19, v45
	v_mul_f32_e32 v20, v20, v45
	v_mul_f32_e32 v21, v21, v45
	v_cmp_lt_i32_e32 vcc, s0, v0
	s_or_b64 s[6:7], vcc, s[6:7]
	v_mul_f32_e32 v72, v100, v47
	v_lshl_add_u32 v47, v63, 2, v62
	v_mul_f32_e32 v49, v101, v49
	v_mul_f32_e32 v51, v102, v51
	v_mul_f32_e32 v53, v103, v53
	ds_read_b128 v[64:67], v47 offset:8192
	ds_read_b128 v[68:71], v47
	s_waitcnt lgkmcnt(1)
	v_add_f32_e32 v63, 1.0, v64
	v_add_f32_e32 v64, 1.0, v65
	v_add_f32_e32 v65, 1.0, v66
	v_add_f32_e32 v66, 1.0, v67
	s_waitcnt lgkmcnt(0)
	v_fma_f32 v49, v64, v49, v69
	v_fma_f32 v51, v65, v51, v70
	v_fmac_f32_e32 v71, v66, v53
	v_fma_f32 v53, v63, v72, v68
	v_cvt_pk_bf16_f32 v64, v53, v49
	v_cvt_pk_bf16_f32 v65, v51, v71
	v_mul_f32_e32 v49, v26, v45
	v_mul_f32_e32 v51, v27, v45
	v_lshlrev_b64 v[26:27], 12, v[54:55]
	v_lshl_add_u64 v[26:27], v[42:43], 0, v[26:27]
	global_store_dwordx2 v[26:27], v[64:65], off
	v_mul_f32_e32 v49, v49, v104
	v_mul_f32_e32 v51, v51, v105
	v_mul_f32_e32 v28, v28, v106
	v_mul_f32_e32 v29, v29, v107
	ds_read_b128 v[64:67], v47 offset:9216
	ds_read_b128 v[68:71], v47 offset:1024
	s_waitcnt lgkmcnt(1)
	v_add_f32_e32 v53, 1.0, v64
	v_add_f32_e32 v63, 1.0, v67
	v_add_f32_e32 v54, 1.0, v65
	v_add_f32_e32 v55, 1.0, v66
	s_waitcnt lgkmcnt(0)
; __device__ __forceinline__ unsigned pk2(float lo, float hi) { unsigned r; asm volatile("v_cvt_pk_bf16_f32 %0, %1, %2" : "=v"(r) : "v"(lo), "v"(hi)); return r; }
; __device__ __forceinline__ void xn_phase(const Params& p, int layer, int which, char* smem) {
;     ...
; #pragma unroll
;         for (int j = 0; j < 8; ++j) { const int c = 4 * (lane + 64 * j); const f32x4 gg = *(const f32x4*)(g + c); float y[4];
; #pragma unroll
;             for (int e = 0; e < 4; ++e) y[e] = v[j][e] * rinv * gg[e] * (1.f + sc[c + e]) + sh[c + e];
;             u32x2 o; o.x = pk2(y[0], y[1]); o.y = pk2(y[2], y[3]); *(u32x2*)(XN + (size_t)row * DM + c) = o; }
	v_fmac_f32_e32 v71, v29, v63
	v_fma_f32 v29, v53, v49, v68
	v_fma_f32 v49, v51, v54, v69
	v_fma_f32 v51, v28, v55, v70
	v_cvt_pk_bf16_f32 v28, v29, v49
	v_cvt_pk_bf16_f32 v29, v51, v71
	global_store_dwordx2 v[26:27], v[28:29], off offset:512
	v_mul_f32_e32 v49, v22, v45
	v_mul_f32_e32 v51, v23, v45
	v_mul_f32_e32 v53, v24, v45
	v_mul_f32_e32 v54, v25, v45
	v_mul_f32_e32 v28, v49, v108
	v_mul_f32_e32 v29, v51, v109
	v_mul_f32_e32 v49, v53, v110
	v_mul_f32_e32 v51, v54, v111
	ds_read_b128 v[22:25], v47 offset:10240
	ds_read_b128 v[64:67], v47 offset:2048
	s_waitcnt lgkmcnt(1)
	v_add_f32_e32 v22, 1.0, v22
	v_add_f32_e32 v23, 1.0, v23
	v_add_f32_e32 v24, 1.0, v24
	v_add_f32_e32 v25, 1.0, v25
	s_waitcnt lgkmcnt(0)
	v_fma_f32 v22, v22, v28, v64
	v_fma_f32 v23, v29, v23, v65
	v_fmac_f32_e32 v67, v51, v25
	v_fma_f32 v24, v49, v24, v66
	v_cvt_pk_bf16_f32 v22, v22, v23
	v_cvt_pk_bf16_f32 v23, v24, v67
	global_store_dwordx2 v[26:27], v[22:23], off offset:1024
	v_mul_f32_e32 v24, v14, v45
	v_mul_f32_e32 v25, v15, v45
	v_mul_f32_e32 v28, v16, v45
	v_mul_f32_e32 v29, v17, v45
	v_mul_f32_e32 v49, v24, v112
	v_mul_f32_e32 v51, v25, v113
	v_mul_f32_e32 v28, v28, v114
	v_mul_f32_e32 v29, v29, v115
	ds_read_b128 v[14:17], v47 offset:11264
	ds_read_b128 v[22:25], v47 offset:3072
	s_waitcnt lgkmcnt(1)
	v_add_f32_e32 v14, 1.0, v14
	v_add_f32_e32 v15, 1.0, v15
	v_add_f32_e32 v16, 1.0, v16
	v_add_f32_e32 v17, 1.0, v17
	s_waitcnt lgkmcnt(0)
	v_fma_f32 v14, v14, v49, v22
	v_fma_f32 v15, v51, v15, v23
	v_fmac_f32_e32 v25, v29, v17
	v_fma_f32 v16, v28, v16, v24
	v_cvt_pk_bf16_f32 v14, v14, v15
	v_cvt_pk_bf16_f32 v15, v16, v25
	global_store_dwordx2 v[26:27], v[14:15], off offset:1536
	v_mul_f32_e32 v22, v18, v116
	v_mul_f32_e32 v23, v19, v117
	v_mul_f32_e32 v24, v20, v118
	v_mul_f32_e32 v25, v21, v119
	ds_read_b128 v[14:17], v47 offset:12288
	ds_read_b128 v[18:21], v47 offset:4096
	s_waitcnt lgkmcnt(1)
	v_add_f32_e32 v14, 1.0, v14
	v_add_f32_e32 v15, 1.0, v15
	v_add_f32_e32 v16, 1.0, v16
	v_add_f32_e32 v17, 1.0, v17
	s_waitcnt lgkmcnt(0)
	v_fma_f32 v14, v14, v22, v18
	v_fma_f32 v15, v23, v15, v19
	v_fmac_f32_e32 v21, v25, v17
	v_fma_f32 v16, v24, v16, v20
	v_cvt_pk_bf16_f32 v14, v14, v15
	v_cvt_pk_bf16_f32 v15, v16, v21
	global_store_dwordx2 v[26:27], v[14:15], off offset:2048
	v_mul_f32_e32 v16, v6, v45
	v_mul_f32_e32 v17, v7, v45
	v_mul_f32_e32 v18, v8, v45
	v_mul_f32_e32 v19, v9, v45
	v_mul_f32_e32 v20, v16, v120
	v_mul_f32_e32 v21, v17, v121
	v_mul_f32_e32 v18, v18, v122
	v_mul_f32_e32 v19, v19, v123
	ds_read_b128 v[6:9], v47 offset:13312
	ds_read_b128 v[14:17], v47 offset:5120
	s_waitcnt lgkmcnt(1)
	v_add_f32_e32 v6, 1.0, v6
	v_add_f32_e32 v7, 1.0, v7
	v_add_f32_e32 v8, 1.0, v8
	v_add_f32_e32 v9, 1.0, v9
	s_waitcnt lgkmcnt(0)
	v_fma_f32 v6, v6, v20, v14
	v_fma_f32 v7, v21, v7, v15
	v_fma_f32 v8, v18, v8, v16
	v_fmac_f32_e32 v17, v19, v9
	v_cvt_pk_bf16_f32 v6, v6, v7
	v_cvt_pk_bf16_f32 v7, v8, v17
	global_store_dwordx2 v[26:27], v[6:7], off offset:2560
	v_mul_f32_e32 v14, v10, v45
	v_mul_f32_e32 v15, v11, v45
	v_mul_f32_e32 v16, v12, v45
	v_mul_f32_e32 v17, v13, v45
	ds_read_b128 v[10:13], v47 offset:14336
	v_mul_f32_e32 v14, v14, v124
	v_mul_f32_e32 v15, v15, v125
	v_mul_f32_e32 v16, v16, v126
	v_mul_f32_e32 v17, v17, v127
	ds_read_b128 v[6:9], v47 offset:6144
	s_waitcnt lgkmcnt(1)
	v_add_f32_e32 v10, 1.0, v10
	v_add_f32_e32 v11, 1.0, v11
	v_add_f32_e32 v12, 1.0, v12
	v_add_f32_e32 v13, 1.0, v13
	s_waitcnt lgkmcnt(0)
	v_fma_f32 v6, v10, v14, v6
	v_fma_f32 v7, v15, v11, v7
	v_fma_f32 v8, v16, v12, v8
	v_fmac_f32_e32 v9, v17, v13
	v_cvt_pk_bf16_f32 v6, v6, v7
	v_cvt_pk_bf16_f32 v7, v8, v9
	global_store_dwordx2 v[26:27], v[6:7], off offset:3072
	ds_read_b128 v[10:13], v47 offset:15360
	v_mul_f32_e32 v14, v2, v45
	v_mul_f32_e32 v15, v3, v45
	v_mul_f32_e32 v16, v4, v45
	v_mul_f32_e32 v17, v5, v45
	ds_read_b128 v[2:5], v47 offset:7168
	s_waitcnt lgkmcnt(1)
	v_add_f32_e32 v10, 1.0, v10
	v_add_f32_e32 v11, 1.0, v11
	v_add_f32_e32 v12, 1.0, v12
	v_add_f32_e32 v13, 1.0, v13
	v_mul_f32_e32 v6, v14, v128
	v_mul_f32_e32 v7, v15, v129
	v_mul_f32_e32 v8, v16, v130
	v_mul_f32_e32 v9, v17, v131
	s_waitcnt lgkmcnt(0)
	v_fma_f32 v2, v10, v6, v2
	v_fma_f32 v3, v7, v11, v3
	v_fma_f32 v4, v8, v12, v4
	v_fmac_f32_e32 v5, v9, v13
	v_cvt_pk_bf16_f32 v2, v2, v3
	v_cvt_pk_bf16_f32 v3, v4, v5
	global_store_dwordx2 v[26:27], v[2:3], off offset:3584
	s_andn2_b64 exec, exec, s[6:7]
	s_cbranch_execz .LBB0_101
